# in-proj GEMM 256x128x64 LDS-DMA with sentinel handshake for LDS-DMA visibility (poison last dword, poll before fragment reads)
# baseline (speedup 1.0000x reference)
.LBB0_270:
	s_and_b64 s[0:1], s[20:21], exec
	s_mov_b32 s10, 208
	s_mov_b32 s11, 20648882
	s_mov_b32 s12, 6656
	s_mov_b32 s1, 2496
	s_cmov_b32 s10, 168
	s_cmov_b32 s11, 25565282
	s_cmov_b32 s12, 5376
	s_cmov_b32 s1, 2016
	v_readlane_b32 s28, v252, 0
	v_readlane_b32 s6, v252, 1
	s_lshr_b32 s6, s6, 3
	s_and_b32 s0, s28, 7
	s_mul_i32 s0, s0, s6
	s_lshr_b32 s28, s28, 3
	s_add_u32 s0, s0, s28
	s_lshl_b32 s6, s6, 3
	s_cmp_ge_u32 s0, s1
	s_cbranch_scc1 .Lgin_done
	v_and_b32_e32 v128, 31, v193
	v_lshlrev_b32_e32 v129, 7, v128
	v_bfe_u32 v130, v193, 1, 3
	v_bfe_u32 v131, v193, 5, 1
	v_xor_b32_e32 v130, v130, v131
	v_bfe_u32 v131, v193, 7, 1
	v_lshl_add_u32 v131, v131, 14, v129
	v_bfe_u32 v132, v193, 6, 1
	v_lshl_add_u32 v132, v132, 13, v129
	v_lshl_add_u32 v144, v130, 4, v131
	v_lshl_add_u32 v211, v130, 4, v132
	v_xor_b32_e32 v128, 2, v130
	v_lshl_add_u32 v146, v128, 4, v131
	v_lshl_add_u32 v248, v128, 4, v132
	v_xor_b32_e32 v128, 4, v130
	v_lshl_add_u32 v147, v128, 4, v131
	v_lshl_add_u32 v249, v128, 4, v132
	v_xor_b32_e32 v128, 6, v130
	v_lshl_add_u32 v210, v128, 4, v131
	v_lshl_add_u32 v250, v128, 4, v132
	v_and_b32_e32 v128, 7, v193
	v_bfe_u32 v129, v193, 4, 3
	v_xor_b32_e32 v128, v128, v129
	v_lshrrev_b32_e32 v129, 3, v193
	v_lshlrev_b32_e32 v129, 11, v129
	v_lshl_add_u32 v251, v128, 4, v129
	v_lshrrev_b32_e32 v128, 6, v193
	v_lshlrev_b32_e32 v128, 10, v128
	s_nop 0
	v_readfirstlane_b32 s22, v128
	v_and_b32_e32 v129, 63, v193
	v_lshl_add_u32 v128, v129, 12, v128
	v_add_u32_e32 v145, 1020, v128
.Lgin_tile:
	s_mul_hi_u32 s28, s0, s11
	s_mul_i32 vcc_lo, s28, s10
	s_sub_u32 vcc_lo, s0, vcc_lo
	s_lshr_b32 vcc_hi, vcc_lo, 3
	s_and_b32 vcc_lo, vcc_lo, 7
	s_lshl_b32 s28, s28, 3
	s_add_u32 s28, s28, vcc_lo
	s_lshl_b32 s20, s28, 19
	s_add_u32 s20, s20, 29876224
	s_add_u32 s20, s94, s20
	s_addc_u32 s21, s95, 0
	s_lshl_b32 s24, vcc_hi, 18
	s_add_u32 s24, s94, s24
	s_addc_u32 s25, s95, 0
	s_mul_i32 s26, s28, s12
	s_lshl_b32 s26, s26, 8
	s_lshl_b32 vcc_hi, vcc_hi, 8
	s_add_u32 s26, s26, vcc_hi
	s_add_u32 s26, s34, s26
	s_addc_u32 s27, s35, 0
	s_mov_b64 exec, 0xfff
	ds_write_b32 v145, v145
	s_mov_b64 exec, -1
	s_waitcnt lgkmcnt(0)
	s_mov_b32 m0, s22
	s_nop 0
	global_load_lds_dwordx4 v251, s[20:21]
	s_add_u32 m0, m0, 0x1000
	s_add_u32 s20, s20, 0x10000
	s_addc_u32 s21, s21, 0
	global_load_lds_dwordx4 v251, s[20:21]
	s_add_u32 m0, m0, 0x1000
	s_add_u32 s20, s20, 0x10000
	s_addc_u32 s21, s21, 0
	global_load_lds_dwordx4 v251, s[20:21]
	s_add_u32 m0, m0, 0x1000
	s_add_u32 s20, s20, 0x10000
	s_addc_u32 s21, s21, 0
	global_load_lds_dwordx4 v251, s[20:21]
	s_add_u32 m0, m0, 0x1000
	s_add_u32 s20, s20, 0x10000
	s_addc_u32 s21, s21, 0
	global_load_lds_dwordx4 v251, s[20:21]
	s_add_u32 m0, m0, 0x1000
	s_add_u32 s20, s20, 0x10000
	s_addc_u32 s21, s21, 0
	global_load_lds_dwordx4 v251, s[20:21]
	s_add_u32 m0, m0, 0x1000
	s_add_u32 s20, s20, 0x10000
	s_addc_u32 s21, s21, 0
	global_load_lds_dwordx4 v251, s[20:21]
	s_add_u32 m0, m0, 0x1000
	s_add_u32 s20, s20, 0x10000
	s_addc_u32 s21, s21, 0
	global_load_lds_dwordx4 v251, s[20:21]
	s_add_u32 m0, m0, 0x1000
	s_sub_u32 s20, s20, 458624
	s_subb_u32 s21, s21, 0
	global_load_lds_dwordx4 v251, s[24:25]
	s_add_u32 m0, m0, 0x1000
	s_add_u32 s24, s24, 0x10000
	s_addc_u32 s25, s25, 0
	global_load_lds_dwordx4 v251, s[24:25]
	s_add_u32 m0, m0, 0x1000
	s_add_u32 s24, s24, 0x10000
	s_addc_u32 s25, s25, 0
	global_load_lds_dwordx4 v251, s[24:25]
	s_add_u32 m0, m0, 0x1000
	s_add_u32 s24, s24, 0x10000
	s_addc_u32 s25, s25, 0
	global_load_lds_dwordx4 v251, s[24:25]
	s_sub_u32 s24, s24, 196480
	s_subb_u32 s25, s25, 0
	v_mov_b32_e32 v0, 0
	v_mov_b32_e32 v1, 0
	v_mov_b32_e32 v2, 0
	v_mov_b32_e32 v3, 0
	v_mov_b32_e32 v4, 0
	v_mov_b32_e32 v5, 0
	v_mov_b32_e32 v6, 0
	v_mov_b32_e32 v7, 0
	v_mov_b32_e32 v8, 0
	v_mov_b32_e32 v9, 0
	v_mov_b32_e32 v10, 0
	v_mov_b32_e32 v11, 0
	v_mov_b32_e32 v12, 0
	v_mov_b32_e32 v13, 0
	v_mov_b32_e32 v14, 0
	v_mov_b32_e32 v15, 0
	v_mov_b32_e32 v16, 0
	v_mov_b32_e32 v17, 0
	v_mov_b32_e32 v18, 0
	v_mov_b32_e32 v19, 0
	v_mov_b32_e32 v20, 0
	v_mov_b32_e32 v21, 0
	v_mov_b32_e32 v22, 0
	v_mov_b32_e32 v23, 0
	v_mov_b32_e32 v24, 0
	v_mov_b32_e32 v25, 0
	v_mov_b32_e32 v26, 0
	v_mov_b32_e32 v27, 0
	v_mov_b32_e32 v28, 0
	v_mov_b32_e32 v29, 0
	v_mov_b32_e32 v30, 0
	v_mov_b32_e32 v31, 0
	v_mov_b32_e32 v32, 0
	v_mov_b32_e32 v33, 0
	v_mov_b32_e32 v34, 0
	v_mov_b32_e32 v35, 0
	v_mov_b32_e32 v36, 0
	v_mov_b32_e32 v37, 0
	v_mov_b32_e32 v38, 0
	v_mov_b32_e32 v39, 0
	v_mov_b32_e32 v40, 0
	v_mov_b32_e32 v41, 0
	v_mov_b32_e32 v42, 0
	v_mov_b32_e32 v43, 0
	v_mov_b32_e32 v44, 0
	v_mov_b32_e32 v45, 0
	v_mov_b32_e32 v46, 0
	v_mov_b32_e32 v47, 0
	v_mov_b32_e32 v48, 0
	v_mov_b32_e32 v49, 0
	v_mov_b32_e32 v50, 0
	v_mov_b32_e32 v51, 0
	v_mov_b32_e32 v52, 0
	v_mov_b32_e32 v53, 0
	v_mov_b32_e32 v54, 0
	v_mov_b32_e32 v55, 0
	v_mov_b32_e32 v56, 0
	v_mov_b32_e32 v57, 0
	v_mov_b32_e32 v58, 0
	v_mov_b32_e32 v59, 0
	v_mov_b32_e32 v60, 0
	v_mov_b32_e32 v61, 0
	v_mov_b32_e32 v62, 0
	v_mov_b32_e32 v63, 0
	v_mov_b32_e32 v64, 0
	v_mov_b32_e32 v65, 0
	v_mov_b32_e32 v66, 0
	v_mov_b32_e32 v67, 0
	v_mov_b32_e32 v68, 0
	v_mov_b32_e32 v69, 0
	v_mov_b32_e32 v70, 0
	v_mov_b32_e32 v71, 0
	v_mov_b32_e32 v72, 0
	v_mov_b32_e32 v73, 0
	v_mov_b32_e32 v74, 0
	v_mov_b32_e32 v75, 0
	v_mov_b32_e32 v76, 0
	v_mov_b32_e32 v77, 0
	v_mov_b32_e32 v78, 0
	v_mov_b32_e32 v79, 0
	v_mov_b32_e32 v80, 0
	v_mov_b32_e32 v81, 0
	v_mov_b32_e32 v82, 0
	v_mov_b32_e32 v83, 0
	v_mov_b32_e32 v84, 0
	v_mov_b32_e32 v85, 0
	v_mov_b32_e32 v86, 0
	v_mov_b32_e32 v87, 0
	v_mov_b32_e32 v88, 0
	v_mov_b32_e32 v89, 0
	v_mov_b32_e32 v90, 0
	v_mov_b32_e32 v91, 0
	v_mov_b32_e32 v92, 0
	v_mov_b32_e32 v93, 0
	v_mov_b32_e32 v94, 0
	v_mov_b32_e32 v95, 0
	v_mov_b32_e32 v96, 0
	v_mov_b32_e32 v97, 0
	v_mov_b32_e32 v98, 0
	v_mov_b32_e32 v99, 0
	v_mov_b32_e32 v100, 0
	v_mov_b32_e32 v101, 0
	v_mov_b32_e32 v102, 0
	v_mov_b32_e32 v103, 0
	v_mov_b32_e32 v104, 0
	v_mov_b32_e32 v105, 0
	v_mov_b32_e32 v106, 0
	v_mov_b32_e32 v107, 0
	v_mov_b32_e32 v108, 0
	v_mov_b32_e32 v109, 0
	v_mov_b32_e32 v110, 0
	v_mov_b32_e32 v111, 0
	v_mov_b32_e32 v112, 0
	v_mov_b32_e32 v113, 0
	v_mov_b32_e32 v114, 0
	v_mov_b32_e32 v115, 0
	v_mov_b32_e32 v116, 0
	v_mov_b32_e32 v117, 0
	v_mov_b32_e32 v118, 0
	v_mov_b32_e32 v119, 0
	v_mov_b32_e32 v120, 0
	v_mov_b32_e32 v121, 0
	v_mov_b32_e32 v122, 0
	v_mov_b32_e32 v123, 0
	v_mov_b32_e32 v124, 0
	v_mov_b32_e32 v125, 0
	v_mov_b32_e32 v126, 0
	v_mov_b32_e32 v127, 0
	s_mov_b32 s16, 16
.Lgin_k:
	s_waitcnt vmcnt(0)
	s_barrier
	v_and_b32_e32 v128, 63, v193
	v_subrev_u32_e32 v129, 48, v128
	v_cmp_gt_u32_e32 vcc, 48, v128
	s_nop 1
	v_cndmask_b32_e32 v128, v129, v128, vcc
	v_lshlrev_b32_e32 v128, 10, v128
	v_add_u32_e32 v128, 1020, v128
	s_mov_b32 s28, 64
.Lgin_poll:
	ds_read_b32 v129, v128
	s_waitcnt lgkmcnt(0)
	v_cmp_eq_u32_e32 vcc, v129, v128
	s_cbranch_vccz .Lgin_pollok
	s_sub_u32 s28, s28, 1
	s_cmp_lg_u32 s28, 0
	s_cbranch_scc1 .Lgin_poll
.Lgin_pollok:
	ds_read_b128 v[128:131], v144 offset:0
	ds_read_b128 v[148:151], v144 offset:4096
	ds_read_b128 v[164:167], v144 offset:8192
	ds_read_b128 v[180:183], v144 offset:12288
	ds_read_b128 v[132:135], v146 offset:0
	ds_read_b128 v[152:155], v146 offset:4096
	ds_read_b128 v[168:171], v146 offset:8192
	ds_read_b128 v[184:187], v146 offset:12288
	ds_read_b128 v[136:139], v147 offset:0
	ds_read_b128 v[156:159], v147 offset:4096
	ds_read_b128 v[172:175], v147 offset:8192
	ds_read_b128 v[188:191], v147 offset:12288
	ds_read_b128 v[140:143], v210 offset:0
	ds_read_b128 v[160:163], v210 offset:4096
	ds_read_b128 v[176:179], v210 offset:8192
	ds_read_b128 v[212:215], v210 offset:12288
	ds_read_b128 v[216:219], v211 offset:32768
	ds_read_b128 v[232:235], v211 offset:36864
	ds_read_b128 v[220:223], v248 offset:32768
	ds_read_b128 v[236:239], v248 offset:36864
	ds_read_b128 v[224:227], v249 offset:32768
	ds_read_b128 v[240:243], v249 offset:36864
	ds_read_b128 v[228:231], v250 offset:32768
	ds_read_b128 v[244:247], v250 offset:36864
	s_waitcnt lgkmcnt(0)
	s_barrier
	s_cmp_eq_u32 s16, 1
	s_cbranch_scc1 .Lgin_nodma
	s_mov_b64 exec, 0xfff
	ds_write_b32 v145, v145
	s_mov_b64 exec, -1
	s_waitcnt lgkmcnt(0)
	s_mov_b32 m0, s22
	s_nop 0
	global_load_lds_dwordx4 v251, s[20:21]
	s_add_u32 m0, m0, 0x1000
	s_add_u32 s20, s20, 0x10000
	s_addc_u32 s21, s21, 0
	global_load_lds_dwordx4 v251, s[20:21]
	s_add_u32 m0, m0, 0x1000
	s_add_u32 s20, s20, 0x10000
	s_addc_u32 s21, s21, 0
	global_load_lds_dwordx4 v251, s[20:21]
	s_add_u32 m0, m0, 0x1000
	s_add_u32 s20, s20, 0x10000
	s_addc_u32 s21, s21, 0
	global_load_lds_dwordx4 v251, s[20:21]
	s_add_u32 m0, m0, 0x1000
	s_add_u32 s20, s20, 0x10000
	s_addc_u32 s21, s21, 0
	global_load_lds_dwordx4 v251, s[20:21]
	s_add_u32 m0, m0, 0x1000
	s_add_u32 s20, s20, 0x10000
	s_addc_u32 s21, s21, 0
	global_load_lds_dwordx4 v251, s[20:21]
	s_add_u32 m0, m0, 0x1000
	s_add_u32 s20, s20, 0x10000
	s_addc_u32 s21, s21, 0
	global_load_lds_dwordx4 v251, s[20:21]
	s_add_u32 m0, m0, 0x1000
	s_add_u32 s20, s20, 0x10000
	s_addc_u32 s21, s21, 0
	global_load_lds_dwordx4 v251, s[20:21]
	s_add_u32 m0, m0, 0x1000
	s_sub_u32 s20, s20, 458624
	s_subb_u32 s21, s21, 0
	global_load_lds_dwordx4 v251, s[24:25]
	s_add_u32 m0, m0, 0x1000
	s_add_u32 s24, s24, 0x10000
	s_addc_u32 s25, s25, 0
	global_load_lds_dwordx4 v251, s[24:25]
	s_add_u32 m0, m0, 0x1000
	s_add_u32 s24, s24, 0x10000
	s_addc_u32 s25, s25, 0
	global_load_lds_dwordx4 v251, s[24:25]
	s_add_u32 m0, m0, 0x1000
	s_add_u32 s24, s24, 0x10000
	s_addc_u32 s25, s25, 0
	global_load_lds_dwordx4 v251, s[24:25]
	s_sub_u32 s24, s24, 196480
	s_subb_u32 s25, s25, 0
.Lgin_nodma:
	v_mfma_f32_32x32x16_bf16 v[0:15], v[216:219], v[128:131], v[0:15]
	v_mfma_f32_32x32x16_bf16 v[16:31], v[232:235], v[128:131], v[16:31]
	v_mfma_f32_32x32x16_bf16 v[32:47], v[216:219], v[148:151], v[32:47]
	v_mfma_f32_32x32x16_bf16 v[48:63], v[232:235], v[148:151], v[48:63]
	v_mfma_f32_32x32x16_bf16 v[64:79], v[216:219], v[164:167], v[64:79]
	v_mfma_f32_32x32x16_bf16 v[80:95], v[232:235], v[164:167], v[80:95]
	v_mfma_f32_32x32x16_bf16 v[96:111], v[216:219], v[180:183], v[96:111]
	v_mfma_f32_32x32x16_bf16 v[112:127], v[232:235], v[180:183], v[112:127]
	v_mfma_f32_32x32x16_bf16 v[0:15], v[220:223], v[132:135], v[0:15]
	v_mfma_f32_32x32x16_bf16 v[16:31], v[236:239], v[132:135], v[16:31]
	v_mfma_f32_32x32x16_bf16 v[32:47], v[220:223], v[152:155], v[32:47]
	v_mfma_f32_32x32x16_bf16 v[48:63], v[236:239], v[152:155], v[48:63]
	v_mfma_f32_32x32x16_bf16 v[64:79], v[220:223], v[168:171], v[64:79]
	v_mfma_f32_32x32x16_bf16 v[80:95], v[236:239], v[168:171], v[80:95]
	v_mfma_f32_32x32x16_bf16 v[96:111], v[220:223], v[184:187], v[96:111]
	v_mfma_f32_32x32x16_bf16 v[112:127], v[236:239], v[184:187], v[112:127]
	v_mfma_f32_32x32x16_bf16 v[0:15], v[224:227], v[136:139], v[0:15]
	v_mfma_f32_32x32x16_bf16 v[16:31], v[240:243], v[136:139], v[16:31]
	v_mfma_f32_32x32x16_bf16 v[32:47], v[224:227], v[156:159], v[32:47]
	v_mfma_f32_32x32x16_bf16 v[48:63], v[240:243], v[156:159], v[48:63]
	v_mfma_f32_32x32x16_bf16 v[64:79], v[224:227], v[172:175], v[64:79]
	v_mfma_f32_32x32x16_bf16 v[80:95], v[240:243], v[172:175], v[80:95]
	v_mfma_f32_32x32x16_bf16 v[96:111], v[224:227], v[188:191], v[96:111]
	v_mfma_f32_32x32x16_bf16 v[112:127], v[240:243], v[188:191], v[112:127]
	v_mfma_f32_32x32x16_bf16 v[0:15], v[228:231], v[140:143], v[0:15]
	v_mfma_f32_32x32x16_bf16 v[16:31], v[244:247], v[140:143], v[16:31]
	v_mfma_f32_32x32x16_bf16 v[32:47], v[228:231], v[160:163], v[32:47]
	v_mfma_f32_32x32x16_bf16 v[48:63], v[244:247], v[160:163], v[48:63]
	v_mfma_f32_32x32x16_bf16 v[64:79], v[228:231], v[176:179], v[64:79]
	v_mfma_f32_32x32x16_bf16 v[80:95], v[244:247], v[176:179], v[80:95]
	v_mfma_f32_32x32x16_bf16 v[96:111], v[228:231], v[212:215], v[96:111]
	v_mfma_f32_32x32x16_bf16 v[112:127], v[244:247], v[212:215], v[112:127]
	s_sub_u32 s16, s16, 1
	s_cmp_lg_u32 s16, 0
	s_cbranch_scc1 .Lgin_k
	s_nop 15
	s_nop 3
	v_and_b32_e32 v215, 31, v193
	v_mul_u32_u24_e32 v212, 0x110, v215
	v_bfe_u32 v215, v193, 5, 1
	v_lshl_add_u32 v212, v215, 3, v212
	v_bfe_u32 v215, v193, 7, 1
	v_mov_b32_e32 v216, 34816
	v_mad_u32_u24 v212, v215, v216, v212
	v_bfe_u32 v215, v193, 6, 1
	v_lshl_add_u32 v212, v215, 7, v212
	v_cvt_pk_bf16_f32 v128, v0, v1
	v_cvt_pk_bf16_f32 v129, v2, v3
	ds_write_b64 v212, v[128:129] offset:0
	v_cvt_pk_bf16_f32 v130, v4, v5
	v_cvt_pk_bf16_f32 v131, v6, v7
	ds_write_b64 v212, v[130:131] offset:16
	v_cvt_pk_bf16_f32 v132, v8, v9
	v_cvt_pk_bf16_f32 v133, v10, v11
	ds_write_b64 v212, v[132:133] offset:32
	v_cvt_pk_bf16_f32 v134, v12, v13
	v_cvt_pk_bf16_f32 v135, v14, v15
	ds_write_b64 v212, v[134:135] offset:48
	v_cvt_pk_bf16_f32 v136, v16, v17
	v_cvt_pk_bf16_f32 v137, v18, v19
	ds_write_b64 v212, v[136:137] offset:64
	v_cvt_pk_bf16_f32 v138, v20, v21
	v_cvt_pk_bf16_f32 v139, v22, v23
	ds_write_b64 v212, v[138:139] offset:80
	v_cvt_pk_bf16_f32 v140, v24, v25
	v_cvt_pk_bf16_f32 v141, v26, v27
	ds_write_b64 v212, v[140:141] offset:96
	v_cvt_pk_bf16_f32 v142, v28, v29
	v_cvt_pk_bf16_f32 v143, v30, v31
	ds_write_b64 v212, v[142:143] offset:112
	v_cvt_pk_bf16_f32 v128, v32, v33
	v_cvt_pk_bf16_f32 v129, v34, v35
	ds_write_b64 v212, v[128:129] offset:8704
	v_cvt_pk_bf16_f32 v130, v36, v37
	v_cvt_pk_bf16_f32 v131, v38, v39
	ds_write_b64 v212, v[130:131] offset:8720
	v_cvt_pk_bf16_f32 v132, v40, v41
	v_cvt_pk_bf16_f32 v133, v42, v43
	ds_write_b64 v212, v[132:133] offset:8736
	v_cvt_pk_bf16_f32 v134, v44, v45
	v_cvt_pk_bf16_f32 v135, v46, v47
	ds_write_b64 v212, v[134:135] offset:8752
	v_cvt_pk_bf16_f32 v136, v48, v49
	v_cvt_pk_bf16_f32 v137, v50, v51
	ds_write_b64 v212, v[136:137] offset:8768
	v_cvt_pk_bf16_f32 v138, v52, v53
	v_cvt_pk_bf16_f32 v139, v54, v55
	ds_write_b64 v212, v[138:139] offset:8784
	v_cvt_pk_bf16_f32 v140, v56, v57
	v_cvt_pk_bf16_f32 v141, v58, v59
	ds_write_b64 v212, v[140:141] offset:8800
	v_cvt_pk_bf16_f32 v142, v60, v61
	v_cvt_pk_bf16_f32 v143, v62, v63
	ds_write_b64 v212, v[142:143] offset:8816
	v_cvt_pk_bf16_f32 v128, v64, v65
	v_cvt_pk_bf16_f32 v129, v66, v67
	ds_write_b64 v212, v[128:129] offset:17408
	v_cvt_pk_bf16_f32 v130, v68, v69
	v_cvt_pk_bf16_f32 v131, v70, v71
	ds_write_b64 v212, v[130:131] offset:17424
	v_cvt_pk_bf16_f32 v132, v72, v73
	v_cvt_pk_bf16_f32 v133, v74, v75
	ds_write_b64 v212, v[132:133] offset:17440
	v_cvt_pk_bf16_f32 v134, v76, v77
	v_cvt_pk_bf16_f32 v135, v78, v79
	ds_write_b64 v212, v[134:135] offset:17456
	v_cvt_pk_bf16_f32 v136, v80, v81
	v_cvt_pk_bf16_f32 v137, v82, v83
	ds_write_b64 v212, v[136:137] offset:17472
	v_cvt_pk_bf16_f32 v138, v84, v85
	v_cvt_pk_bf16_f32 v139, v86, v87
	ds_write_b64 v212, v[138:139] offset:17488
	v_cvt_pk_bf16_f32 v140, v88, v89
	v_cvt_pk_bf16_f32 v141, v90, v91
	ds_write_b64 v212, v[140:141] offset:17504
	v_cvt_pk_bf16_f32 v142, v92, v93
	v_cvt_pk_bf16_f32 v143, v94, v95
	ds_write_b64 v212, v[142:143] offset:17520
	v_cvt_pk_bf16_f32 v128, v96, v97
	v_cvt_pk_bf16_f32 v129, v98, v99
	ds_write_b64 v212, v[128:129] offset:26112
	v_cvt_pk_bf16_f32 v130, v100, v101
	v_cvt_pk_bf16_f32 v131, v102, v103
	ds_write_b64 v212, v[130:131] offset:26128
	v_cvt_pk_bf16_f32 v132, v104, v105
	v_cvt_pk_bf16_f32 v133, v106, v107
	ds_write_b64 v212, v[132:133] offset:26144
	v_cvt_pk_bf16_f32 v134, v108, v109
	v_cvt_pk_bf16_f32 v135, v110, v111
	ds_write_b64 v212, v[134:135] offset:26160
	v_cvt_pk_bf16_f32 v136, v112, v113
	v_cvt_pk_bf16_f32 v137, v114, v115
	ds_write_b64 v212, v[136:137] offset:26176
	v_cvt_pk_bf16_f32 v138, v116, v117
	v_cvt_pk_bf16_f32 v139, v118, v119
	ds_write_b64 v212, v[138:139] offset:26192
	v_cvt_pk_bf16_f32 v140, v120, v121
	v_cvt_pk_bf16_f32 v141, v122, v123
	ds_write_b64 v212, v[140:141] offset:26208
	v_cvt_pk_bf16_f32 v142, v124, v125
	v_cvt_pk_bf16_f32 v143, v126, v127
	ds_write_b64 v212, v[142:143] offset:26224
	s_waitcnt lgkmcnt(0)
	s_barrier
	v_lshrrev_b32_e32 v215, 4, v193
	v_and_b32_e32 v216, 15, v193
	v_mul_u32_u24_e32 v213, 0x110, v215
	v_lshl_add_u32 v213, v216, 4, v213
	v_mul_lo_u32 v214, v215, s12
	v_lshl_add_u32 v214, v216, 4, v214
	s_lshl_b32 s28, s12, 4
	ds_read_b128 v[148:151], v213 offset:0
	ds_read_b128 v[152:155], v213 offset:4352
	ds_read_b128 v[156:159], v213 offset:8704
	ds_read_b128 v[160:163], v213 offset:13056
	ds_read_b128 v[164:167], v213 offset:17408
	ds_read_b128 v[168:171], v213 offset:21760
	ds_read_b128 v[172:175], v213 offset:26112
	ds_read_b128 v[176:179], v213 offset:30464
	ds_read_b128 v[180:183], v213 offset:34816
	ds_read_b128 v[184:187], v213 offset:39168
	ds_read_b128 v[188:191], v213 offset:43520
	ds_read_b128 v[220:223], v213 offset:47872
	ds_read_b128 v[224:227], v213 offset:52224
	ds_read_b128 v[228:231], v213 offset:56576
	ds_read_b128 v[232:235], v213 offset:60928
	ds_read_b128 v[236:239], v213 offset:65280
	s_waitcnt lgkmcnt(15)
	global_store_dwordx4 v214, v[148:151], s[26:27]
	s_add_u32 s26, s26, s28
	s_addc_u32 s27, s27, 0
	s_waitcnt lgkmcnt(14)
	global_store_dwordx4 v214, v[152:155], s[26:27]
	s_add_u32 s26, s26, s28
	s_addc_u32 s27, s27, 0
	s_waitcnt lgkmcnt(13)
	global_store_dwordx4 v214, v[156:159], s[26:27]
	s_add_u32 s26, s26, s28
	s_addc_u32 s27, s27, 0
	s_waitcnt lgkmcnt(12)
	global_store_dwordx4 v214, v[160:163], s[26:27]
	s_add_u32 s26, s26, s28
	s_addc_u32 s27, s27, 0
	s_waitcnt lgkmcnt(11)
	global_store_dwordx4 v214, v[164:167], s[26:27]
	s_add_u32 s26, s26, s28
	s_addc_u32 s27, s27, 0
	s_waitcnt lgkmcnt(10)
	global_store_dwordx4 v214, v[168:171], s[26:27]
	s_add_u32 s26, s26, s28
	s_addc_u32 s27, s27, 0
	s_waitcnt lgkmcnt(9)
	global_store_dwordx4 v214, v[172:175], s[26:27]
	s_add_u32 s26, s26, s28
	s_addc_u32 s27, s27, 0
	s_waitcnt lgkmcnt(8)
	global_store_dwordx4 v214, v[176:179], s[26:27]
	s_add_u32 s26, s26, s28
	s_addc_u32 s27, s27, 0
	s_waitcnt lgkmcnt(7)
	global_store_dwordx4 v214, v[180:183], s[26:27]
	s_add_u32 s26, s26, s28
	s_addc_u32 s27, s27, 0
	s_waitcnt lgkmcnt(6)
	global_store_dwordx4 v214, v[184:187], s[26:27]
	s_add_u32 s26, s26, s28
	s_addc_u32 s27, s27, 0
	s_waitcnt lgkmcnt(5)
	global_store_dwordx4 v214, v[188:191], s[26:27]
	s_add_u32 s26, s26, s28
	s_addc_u32 s27, s27, 0
	s_waitcnt lgkmcnt(4)
	global_store_dwordx4 v214, v[220:223], s[26:27]
	s_add_u32 s26, s26, s28
	s_addc_u32 s27, s27, 0
	s_waitcnt lgkmcnt(3)
	global_store_dwordx4 v214, v[224:227], s[26:27]
	s_add_u32 s26, s26, s28
	s_addc_u32 s27, s27, 0
	s_waitcnt lgkmcnt(2)
	global_store_dwordx4 v214, v[228:231], s[26:27]
	s_add_u32 s26, s26, s28
	s_addc_u32 s27, s27, 0
	s_waitcnt lgkmcnt(1)
	global_store_dwordx4 v214, v[232:235], s[26:27]
	s_add_u32 s26, s26, s28
	s_addc_u32 s27, s27, 0
	s_waitcnt lgkmcnt(0)
	global_store_dwordx4 v214, v[236:239], s[26:27]
	s_barrier
	s_add_u32 s0, s0, s6
	s_cmp_lt_u32 s0, s1
	s_cbranch_scc1 .Lgin_tile
	v_mov_b32_e32 v145, 0
